# P3 delta items segment (c): the 4 B fragments of each k-step read together with counted lgkmcnt waits
# baseline (speedup 1.0000x reference)
.LBB0_333:
	s_waitcnt lgkmcnt(0)
	s_barrier
	ds_read_b128 v[34:37], v213
	ds_read_b128 v[38:41], v213 offset:17408
	ds_read_b128 v[42:45], v214
	ds_read_b128 v[50:53], v214 offset:4352
	ds_read_b128 v[58:61], v214 offset:8704
	ds_read_b128 v[66:69], v214 offset:13056
	s_waitcnt lgkmcnt(3)
	v_mfma_f32_16x16x32_bf16 v[46:49], v[34:37], v[42:45], 0
	v_readlane_b32 s2, v250, 14
	v_readlane_b32 s3, v250, 15
	v_mfma_f32_16x16x32_bf16 v[42:45], v[38:41], v[42:45], 0
	s_waitcnt lgkmcnt(2)
	v_mfma_f32_16x16x32_bf16 v[54:57], v[34:37], v[50:53], 0
	v_mfma_f32_16x16x32_bf16 v[50:53], v[38:41], v[50:53], 0
	s_waitcnt lgkmcnt(1)
	v_mfma_f32_16x16x32_bf16 v[62:65], v[34:37], v[58:61], 0
	v_mfma_f32_16x16x32_bf16 v[58:61], v[38:41], v[58:61], 0
	s_waitcnt lgkmcnt(0)
	v_mfma_f32_16x16x32_bf16 v[34:37], v[34:37], v[66:69], 0
	v_mfma_f32_16x16x32_bf16 v[38:41], v[38:41], v[66:69], 0
	ds_read_b128 v[66:69], v213 offset:64
	ds_read_b128 v[96:99], v213 offset:17472
	ds_read_b128 v[100:103], v214 offset:64
	ds_read_b128 v[2:5], v214 offset:4416
	ds_read_b128 v[6:9], v214 offset:8768
	ds_read_b128 v[10:13], v214 offset:13120
	s_waitcnt lgkmcnt(3)
	v_mfma_f32_16x16x32_bf16 v[46:49], v[66:69], v[100:103], v[46:49]
	v_mfma_f32_16x16x32_bf16 v[42:45], v[96:99], v[100:103], v[42:45]
	s_waitcnt lgkmcnt(2)
	v_mfma_f32_16x16x32_bf16 v[54:57], v[66:69], v[2:5], v[54:57]
	v_mfma_f32_16x16x32_bf16 v[50:53], v[96:99], v[2:5], v[50:53]
	s_waitcnt lgkmcnt(1)
	v_mfma_f32_16x16x32_bf16 v[62:65], v[66:69], v[6:9], v[62:65]
	v_mfma_f32_16x16x32_bf16 v[58:61], v[96:99], v[6:9], v[58:61]
	s_waitcnt lgkmcnt(0)
	v_mfma_f32_16x16x32_bf16 v[34:37], v[66:69], v[10:13], v[34:37]
	v_mfma_f32_16x16x32_bf16 v[38:41], v[96:99], v[10:13], v[38:41]
	ds_read_b128 v[66:69], v213 offset:128
	ds_read_b128 v[96:99], v213 offset:17536
	ds_read_b128 v[100:103], v214 offset:128
	ds_read_b128 v[2:5], v214 offset:4480
	ds_read_b128 v[6:9], v214 offset:8832
	ds_read_b128 v[10:13], v214 offset:13184
	s_waitcnt lgkmcnt(3)
	v_mfma_f32_16x16x32_bf16 v[46:49], v[66:69], v[100:103], v[46:49]
	v_mfma_f32_16x16x32_bf16 v[42:45], v[96:99], v[100:103], v[42:45]
	s_waitcnt lgkmcnt(2)
	v_mfma_f32_16x16x32_bf16 v[54:57], v[66:69], v[2:5], v[54:57]
	v_mfma_f32_16x16x32_bf16 v[50:53], v[96:99], v[2:5], v[50:53]
	s_waitcnt lgkmcnt(1)
	v_mfma_f32_16x16x32_bf16 v[104:107], v[66:69], v[6:9], v[62:65]
	v_mfma_f32_16x16x32_bf16 v[100:103], v[96:99], v[6:9], v[58:61]
	s_nop 2
	s_waitcnt lgkmcnt(0)
	v_mfma_f32_16x16x32_bf16 v[34:37], v[66:69], v[10:13], v[34:37]
	v_mfma_f32_16x16x32_bf16 v[66:69], v[96:99], v[10:13], v[38:41]
	s_nop 2
	ds_read_b128 v[38:41], v213 offset:192
	ds_read_b128 v[96:99], v213 offset:17600
	ds_read_b128 v[58:61], v214 offset:192
	ds_read_b128 v[2:5], v214 offset:4544
	ds_read_b128 v[6:9], v214 offset:8896
	ds_read_b128 v[10:13], v214 offset:13248
	s_waitcnt lgkmcnt(3)
	v_mfma_f32_16x16x32_bf16 v[62:65], v[38:41], v[58:61], v[46:49]
	v_mfma_f32_16x16x32_bf16 v[58:61], v[96:99], v[58:61], v[42:45]
	s_nop 2
	s_waitcnt lgkmcnt(2)
	v_mfma_f32_16x16x32_bf16 v[54:57], v[38:41], v[2:5], v[54:57]
	v_mfma_f32_16x16x32_bf16 v[50:53], v[96:99], v[2:5], v[50:53]
	s_waitcnt lgkmcnt(1)
	v_mfma_f32_16x16x32_bf16 v[46:49], v[38:41], v[6:9], v[104:107]
	v_mfma_f32_16x16x32_bf16 v[42:45], v[96:99], v[6:9], v[100:103]
	s_nop 2
	s_waitcnt lgkmcnt(0)
	v_mfma_f32_16x16x32_bf16 v[38:41], v[38:41], v[10:13], v[34:37]
	v_mfma_f32_16x16x32_bf16 v[34:37], v[96:99], v[10:13], v[66:69]
	ds_read2st64_b32 v[96:97], v147 offset0:136 offset1:138
	s_nop 1
	ds_read_b32 v66, v148 offset:34816
	v_cndmask_b32_e64 v68, 0, 1, s[2:3]
	v_cmp_ne_u32_e64 s[68:69], 1, v68
	s_waitcnt lgkmcnt(0)
	v_sub_f32_e32 v66, v66, v96
	v_mul_f32_e64 v66, |v66|, s51
	v_exp_f32_e32 v67, v66
	v_mov_b32_e32 v66, 0
	s_and_saveexec_b64 s[2:3], s[4:5]
	s_cbranch_execz .LBB0_337
	s_and_b64 vcc, exec, s[68:69]
	v_mov_b32_e32 v66, v97
	s_cbranch_vccnz .LBB0_336
	ds_read_b32 v66, v148 offset:35328
